# RWKV: stage-1 causal masks by one signed compare per element, cumulative-decay stage with all LDS reads issued first, NT4 relaid conflict-free
# speedup vs baseline: 1.0220x; 1.0013x over previous
; __device__ __forceinline__ void rwkv_chain(LAS unsigned char* lds, int cid, const bf16_t* P0, const float* mu, const float* w0, const float* w2, const float* a0, const float* a2, ...
;     ...
;         { RW_IDS if (tid < 64) { float lw[32];
; #pragma unroll
;             for (int s = 0; s < 32; ++s) lw[s] = wS[(dir ? 31 - s : s) * 64 + tid];
; #pragma unroll
;             for (int s = 1; s < 32; ++s) lw[s] += lw[s - 1];
; #pragma unroll
;             for (int s = 0; s < 32; ++s) wS[(dir ? 31 - s : s) * 64 + tid] = lw[s]; } }
.LBB0_514:
	s_or_b64 exec, exec, s[12:13]
	v_mov_b32_e32 v8, v200
	s_waitcnt lgkmcnt(0)
	s_barrier
	s_nop 0
	v_cmp_gt_i32_e32 vcc, 64, v8
	s_and_saveexec_b64 s[12:13], vcc
	s_cbranch_execz .LBB0_516
	v_lshl_add_u32 v8, v8, 2, 0
	v_add_u32_e32 v9, s93, v8
	v_add_u32_e32 v10, s94, v8
	v_add_u32_e32 v11, s95, v8
	v_add_u32_e32 v12, s96, v8
	v_add_u32_e32 v13, s97, v8
	v_add_u32_e32 v14, s22, v8
	v_add_u32_e32 v15, s23, v8
	v_add_u32_e32 v16, s18, v8
	v_add_u32_e32 v24, s19, v8
	v_add_u32_e32 v25, s2, v8
	v_add_u32_e32 v26, s3, v8
	v_add_u32_e32 v27, s56, v8
	v_add_u32_e32 v28, s57, v8
	v_add_u32_e32 v29, s0, v8
	v_add_u32_e32 v30, s1, v8
	v_add_u32_e32 v31, s4, v8
	v_add_u32_e32 v117, s9, v8
	v_add_u32_e32 v118, s5, v8
	v_add_u32_e32 v119, s60, v8
	v_add_u32_e32 v120, s61, v8
	v_add_u32_e32 v121, s63, v8
	v_add_u32_e32 v122, s64, v8
	v_add_u32_e32 v123, s65, v8
	v_add_u32_e32 v124, s66, v8
	v_add_u32_e32 v133, s67, v8
	v_add_u32_e32 v134, s68, v8
	v_add_u32_e32 v135, s69, v8
	v_add_u32_e32 v136, s70, v8
	v_add_u32_e32 v137, s71, v8
	v_add_u32_e32 v138, s72, v8
	v_add_u32_e32 v139, s73, v8
	v_add_u32_e32 v8, s8, v8
	ds_read_b32 v9, v9 offset:24576
	ds_read_b32 v17, v10 offset:24576
	ds_read_b32 v18, v11 offset:24576
	ds_read_b32 v19, v12 offset:24576
	ds_read_b32 v20, v13 offset:24576
	ds_read_b32 v21, v14 offset:24576
	ds_read_b32 v22, v15 offset:24576
	ds_read_b32 v23, v16 offset:24576
	ds_read_b32 v32, v24 offset:24576
	ds_read_b32 v33, v25 offset:24576
	ds_read_b32 v34, v26 offset:24576
	ds_read_b32 v35, v27 offset:24576
	ds_read_b32 v39, v28 offset:24576
	ds_read_b32 v114, v29 offset:24576
	ds_read_b32 v115, v30 offset:24576
	ds_read_b32 v116, v31 offset:28416
	ds_read_b32 v125, v117 offset:28672
	ds_read_b32 v126, v118 offset:24576
	ds_read_b32 v127, v119 offset:24576
	ds_read_b32 v128, v120 offset:24576
	ds_read_b32 v129, v121 offset:24576
	ds_read_b32 v130, v122 offset:24576
	ds_read_b32 v131, v123 offset:24576
	ds_read_b32 v132, v124 offset:24576
	ds_read_b32 v140, v133 offset:24576
	ds_read_b32 v141, v134 offset:24576
	ds_read_b32 v142, v135 offset:24576
	ds_read_b32 v143, v136 offset:24576
	ds_read_b32 v144, v137 offset:24576
	ds_read_b32 v145, v138 offset:24576
	ds_read_b32 v146, v139 offset:24576
	ds_read_b32 v147, v8 offset:24576
	s_waitcnt lgkmcnt(15)
	v_add_f32_e32 v9, v9, v17
	v_add_f32_e32 v17, v9, v18
	v_add_f32_e32 v18, v17, v19
	v_add_f32_e32 v19, v18, v20
	v_add_f32_e32 v20, v19, v21
	v_add_f32_e32 v21, v20, v22
	v_add_f32_e32 v22, v21, v23
	v_add_f32_e32 v23, v22, v32
	v_add_f32_e32 v32, v23, v33
	v_add_f32_e32 v33, v32, v34
	v_add_f32_e32 v34, v33, v35
	v_add_f32_e32 v35, v34, v39
	v_add_f32_e32 v39, v35, v114
	v_add_f32_e32 v114, v39, v115
	v_add_f32_e32 v115, v114, v116
	v_add_f32_e32 v116, v115, v125
	s_waitcnt lgkmcnt(14)
	v_add_f32_e32 v125, v116, v126
	s_waitcnt lgkmcnt(13)
	v_add_f32_e32 v126, v125, v127
	s_waitcnt lgkmcnt(12)
	v_add_f32_e32 v127, v126, v128
	s_waitcnt lgkmcnt(11)
	v_add_f32_e32 v128, v127, v129
	s_waitcnt lgkmcnt(10)
	v_add_f32_e32 v129, v128, v130
	s_waitcnt lgkmcnt(9)
	v_add_f32_e32 v130, v129, v131
	s_waitcnt lgkmcnt(8)
	v_add_f32_e32 v131, v130, v132
	s_waitcnt lgkmcnt(7)
	v_add_f32_e32 v132, v131, v140
	s_waitcnt lgkmcnt(6)
	v_add_f32_e32 v140, v132, v141
	s_waitcnt lgkmcnt(5)
	v_add_f32_e32 v141, v140, v142
	s_waitcnt lgkmcnt(4)
	v_add_f32_e32 v142, v141, v143
	s_waitcnt lgkmcnt(3)
	v_add_f32_e32 v143, v142, v144
	s_waitcnt lgkmcnt(2)
	v_add_f32_e32 v144, v143, v145
	s_waitcnt lgkmcnt(1)
	v_add_f32_e32 v145, v144, v146
	s_waitcnt lgkmcnt(0)
	v_add_f32_e32 v146, v145, v147
	ds_write_b32 v10, v9 offset:24576
	ds_write_b32 v11, v17 offset:24576
	ds_write_b32 v12, v18 offset:24576
	ds_write_b32 v13, v19 offset:24576
	ds_write_b32 v14, v20 offset:24576
	ds_write_b32 v15, v21 offset:24576
	ds_write_b32 v16, v22 offset:24576
	ds_write_b32 v24, v23 offset:24576
	ds_write_b32 v25, v32 offset:24576
	ds_write_b32 v26, v33 offset:24576
	ds_write_b32 v27, v34 offset:24576
	ds_write_b32 v28, v35 offset:24576
	ds_write_b32 v29, v39 offset:24576
	ds_write_b32 v30, v114 offset:24576
	ds_write_b32 v31, v115 offset:28416
	ds_write_b32 v117, v116 offset:28672
	ds_write_b32 v118, v125 offset:24576
	ds_write_b32 v119, v126 offset:24576
	ds_write_b32 v120, v127 offset:24576
	ds_write_b32 v121, v128 offset:24576
	ds_write_b32 v122, v129 offset:24576
	ds_write_b32 v123, v130 offset:24576
	ds_write_b32 v124, v131 offset:24576
	ds_write_b32 v133, v132 offset:24576
	ds_write_b32 v134, v140 offset:24576
	ds_write_b32 v135, v141 offset:24576
	ds_write_b32 v136, v142 offset:24576
	ds_write_b32 v137, v143 offset:24576
	ds_write_b32 v138, v144 offset:24576
	ds_write_b32 v139, v145 offset:24576
	ds_write_b32 v8, v146 offset:24576
; __device__ __forceinline__ void rwkv_chain(LAS unsigned char* lds, int cid, const bf16_t* P0, const float* mu, const float* w0, const float* w2, const float* a0, const float* a2, ...
;     ...
;         { RW_IDS const int s = tid >> 4, c0 = (tid & 15) * 4; const int tok = dir ? 31 - s : s, tokp = dir ? tok + 1 : tok - 1;
;           const f32x4 cum = *(const LAS f32x4*)(wS + tok * 64 + c0); f32x4 cump = (f32x4){0.f, 0.f, 0.f, 0.f}; if (s > 0) cump = *(const LAS f32x4*)(wS + tokp * 64 + c0);
;           const f32x4 nk4 = *(const LAS f32x4*)(nkS + tok * 64 + c0), b4 = *(const LAS f32x4*)(bS + tok * 64 + c0), k4 = *(const LAS f32x4*)(kS + tok * 64 + c0), r4 = *(const LAS f32x4*)(rS + tok * 64 + c0), v4 = *(const LAS f32x4*)(vS + tok * 64 + c0);
;           float ta[4], tb[4], tk[4], tr[4];
; #pragma unroll
;           for (int i = 0; i < 4; ++i) { const float g = __expf(cum[i]), gp = __expf(cump[i]), ig = __expf(-cum[i]);
;               ta[i] = nk4[i] * gp; tb[i] = b4[i] * ig; tk[i] = k4[i] * ig; tr[i] = r4[i] * g;
;               BtT[(c0 + i) * 40 + s] = (bf16_t)f2bf(tb[i]); KtT[(c0 + i) * 40 + s] = (bf16_t)f2bf(tk[i]); VT[(c0 + i) * 40 + s] = (bf16_t)f2bf(v4[i]);
;               if (s == 31) gL[c0 + i] = g; }
;           u32x2 w; w.x = pk2(ta[0], ta[1]); w.y = pk2(ta[2], ta[3]); *(LAS u32x2*)(At + s * 72 + c0) = w;
;           w.x = pk2(tb[0], tb[1]); w.y = pk2(tb[2], tb[3]); *(LAS u32x2*)(Bt + s * 72 + c0) = w;
;           w.x = pk2(tk[0], tk[1]); w.y = pk2(tk[2], tk[3]); *(LAS u32x2*)(Kt + s * 72 + c0) = w;
;           w.x = pk2(tr[0], tr[1]); w.y = pk2(tr[2], tr[3]); *(LAS u32x2*)(Rt + s * 72 + c0) = w; }
;         __syncthreads();
;         { RW_IDS const int mat = wid >> 1, mt = wid & 1; const LAS bf16_t* Aop = (mat < 2) ? At : Rt; const LAS bf16_t* Bop = (mat & 1) ? Kt : Bt;
; #pragma unroll
;           for (int nt = 0; nt < 2; ++nt) { f32x4 acc = (f32x4){0.f, 0.f, 0.f, 0.f};
; #pragma unroll
;               for (int ks = 0; ks < 2; ++ks) acc = mfma16(ldsfrag(Bop, 72, nt * 16, ks * 32, fr, fq), ldsfrag(Aop, 72, mt * 16, ks * 32, fr, fq), acc);
;               const int srow = mt * 16 + fr;
; #pragma unroll
;               for (int e = 0; e < 4; ++e) { const int i = nt * 16 + fq * 4 + e; const bool keep = (mat < 2) ? (i < srow) : (i <= srow); if (!keep) acc[e] = 0.f; }
;               if (mat == 0) {
; #pragma unroll
.LBB0_516:
	s_or_b64 exec, exec, s[12:13]
	v_mov_b32_e32 v8, v200
	s_waitcnt lgkmcnt(0)
	s_barrier
	v_mov_b32_e32 v9, 0
	v_ashrrev_i32_e32 v39, 4, v8
	v_lshlrev_b32_e32 v8, 2, v8
	v_and_b32_e32 v114, 60, v8
	v_sub_u32_e32 v8, 31, v39
	v_cndmask_b32_e64 v12, v39, v8, s[10:11]
	v_lshlrev_b32_e32 v8, 8, v12
	v_lshlrev_b32_e32 v13, 2, v114
	v_add3_u32 v24, 0, v8, v13
	ds_read_b128 v[20:23], v24 offset:24576
	v_cmp_lt_i32_e32 vcc, 0, v39
	v_mov_b32_e32 v8, 0
	v_mov_b32_e32 v10, 0
	v_mov_b32_e32 v11, 0
	s_and_saveexec_b64 s[12:13], vcc
	v_add_lshl_u32 v8, v12, s90, 8
	v_add3_u32 v8, 0, v8, v13
	ds_read_b128 v[8:11], v8 offset:24576
	s_or_b64 exec, exec, s[12:13]
	s_waitcnt lgkmcnt(0)
	v_mul_f32_e32 v115, 0xbfb8aa3b, v20
	v_exp_f32_e32 v116, v115
	ds_read_b128 v[12:15], v24 offset:32768
	ds_read_b128 v[28:31], v24 offset:40960
	ds_read_b128 v[32:35], v24 offset:8192
	ds_read_b128 v[16:19], v24
	ds_read_b128 v[24:27], v24 offset:16384
	v_mul_f32_e32 v20, 0x3fb8aa3b, v20
	v_exp_f32_e32 v115, v20
	s_waitcnt lgkmcnt(3)
	v_mul_f32_e32 v28, v116, v28
	s_waitcnt lgkmcnt(2)
	v_mul_f32_e32 v20, v116, v32
	v_mad_u32_u24 v116, v114, 40, v39
	v_lshl_add_u32 v116, v116, 1, 0
	v_cvt_pk_bf16_f32 v32, v28, s0
	v_add_u32_e32 v117, 0x1c400, v116
	v_cmp_eq_u32_e32 vcc, 31, v39
	ds_write_b16 v117, v32
	v_cvt_pk_bf16_f32 v32, v20, s0
	v_add_u32_e32 v118, 0x1d800, v116
	s_waitcnt lgkmcnt(1)
	v_cvt_pk_bf16_f32 v24, v24, s0
	v_add_u32_e32 v119, 0x1ec00, v116
	v_lshl_add_u32 v116, v114, 2, 0
	ds_write_b16 v118, v32
	ds_write_b16 v119, v24
	s_and_saveexec_b64 s[12:13], vcc
	v_add_u32_e32 v24, 0x25a00, v116
	ds_write_b32 v24, v115
	s_or_b64 exec, exec, s[12:13]
	v_mul_f32_e32 v24, 0xbfb8aa3b, v21
	v_exp_f32_e32 v120, v24
	v_mul_f32_e32 v21, 0x3fb8aa3b, v21
	v_exp_f32_e32 v32, v21
	v_cvt_pk_bf16_f32 v25, v25, s0
	v_mul_f32_e32 v24, v120, v29
	v_mul_f32_e32 v21, v120, v33
	v_cvt_pk_bf16_f32 v29, v24, s0
	ds_write_b16 v117, v29 offset:80
	v_cvt_pk_bf16_f32 v29, v21, s0
	ds_write_b16 v118, v29 offset:80
	ds_write_b16 v119, v25 offset:80
	s_and_saveexec_b64 s[12:13], vcc
	v_add_u32_e32 v25, 0x25a04, v116
	ds_write_b32 v25, v32
	s_or_b64 exec, exec, s[12:13]
	v_mul_f32_e32 v25, 0xbfb8aa3b, v22
	v_exp_f32_e32 v33, v25
	v_mul_f32_e32 v22, 0x3fb8aa3b, v22
	v_exp_f32_e32 v29, v22
	v_cvt_pk_bf16_f32 v26, v26, s0
	v_mul_f32_e32 v25, v33, v30
	v_mul_f32_e32 v22, v33, v34
	v_cvt_pk_bf16_f32 v30, v25, s0
	ds_write_b16 v117, v30 offset:160
	v_cvt_pk_bf16_f32 v30, v22, s0
	ds_write_b16 v118, v30 offset:160
	ds_write_b16 v119, v26 offset:160
	s_and_saveexec_b64 s[12:13], vcc
	v_add_u32_e32 v26, 0x25a08, v116
	ds_write_b32 v26, v29
	s_or_b64 exec, exec, s[12:13]
	v_mul_f32_e32 v26, 0xbfb8aa3b, v23
	v_exp_f32_e32 v33, v26
	v_mul_f32_e32 v23, 0x3fb8aa3b, v23
	v_exp_f32_e32 v30, v23
	v_cvt_pk_bf16_f32 v27, v27, s0
	v_mul_f32_e32 v26, v33, v31
	v_mul_f32_e32 v23, v33, v35
	v_cvt_pk_bf16_f32 v31, v26, s0
	ds_write_b16 v117, v31 offset:240
	v_cvt_pk_bf16_f32 v31, v23, s0
	ds_write_b16 v118, v31 offset:240
	ds_write_b16 v119, v27 offset:240
	s_and_saveexec_b64 s[12:13], vcc
	v_add_u32_e32 v27, 0x25a0c, v116
	ds_write_b32 v27, v30
	s_or_b64 exec, exec, s[12:13]
	v_mul_f32_e32 v11, 0x3fb8aa3b, v11
	v_mul_f32_e32 v10, 0x3fb8aa3b, v10
	v_mul_f32_e32 v9, 0x3fb8aa3b, v9
	v_mul_f32_e32 v8, 0x3fb8aa3b, v8
	v_exp_f32_e32 v11, v11
	v_exp_f32_e32 v10, v10
	v_exp_f32_e32 v9, v9
	v_exp_f32_e32 v8, v8
	v_mul_f32_e32 v11, v15, v11
	v_mul_f32_e32 v10, v14, v10
	v_mul_f32_e32 v9, v13, v9
	v_mul_f32_e32 v8, v12, v8
	v_cvt_pk_bf16_f32 v8, v8, v9
	v_cvt_pk_bf16_f32 v9, v10, v11
	v_mul_lo_u32 v10, v39, s76
	v_lshlrev_b32_e32 v11, 1, v114
	v_mul_f32_e32 v12, v115, v16
	v_add3_u32 v16, s79, v10, v11
	ds_write_b64 v16, v[8:9]
	v_cvt_pk_bf16_f32 v8, v28, v24
	v_cvt_pk_bf16_f32 v9, v25, v26
	v_add3_u32 v16, s80, v10, v11
	v_mul_f32_e32 v15, v30, v19
	v_mul_f32_e32 v14, v29, v18
	v_mul_f32_e32 v13, v32, v17
	ds_write_b64 v16, v[8:9]
	v_cvt_pk_bf16_f32 v8, v20, v21
	v_cvt_pk_bf16_f32 v9, v22, v23
	v_add3_u32 v16, s81, v10, v11
	ds_write_b64 v16, v[8:9]
	v_cvt_pk_bf16_f32 v8, v12, v13
	v_cvt_pk_bf16_f32 v9, v14, v15
	v_add3_u32 v10, s82, v10, v11
	ds_write_b64 v10, v[8:9]
	v_mov_b32_e32 v8, v200
	s_waitcnt lgkmcnt(0)
	s_barrier
	s_nop 0
	v_readfirstlane_b32 s7, v8
	s_ashr_i32 s48, s7, 7
	s_cmp_lt_i32 s48, 2
	s_cselect_b64 s[12:13], -1, 0
	s_and_b64 s[14:15], s[12:13], exec
	v_bfe_u32 v13, v8, 4, 2
	s_cselect_b32 s14, s79, s82
	s_bitcmp0_b32 s7, 7
	s_cselect_b32 s15, s80, s81
	v_lshlrev_b32_e32 v9, 4, v13
	v_add_u32_e32 v11, s15, v9
	s_lshr_b32 s15, s7, 2
	s_cmpk_gt_u32 s7, 0x7f
	s_cselect_b64 s[16:17], -1, 0
	s_cmp_eq_u32 s48, 2
	s_mov_b32 s7, 0x24600
	s_cselect_b32 s7, s7, 0x25000
	s_cmp_lg_u32 s48, 1
	v_and_b32_e32 v10, 15, v8
	s_cselect_b32 s7, s7, 0x23c00
	v_and_or_b32 v8, s15, 16, v10
	v_mov_b32_e32 v12, s14
	s_add_i32 s7, s7, 0
	v_mad_u32_u24 v12, v8, s76, v12
	v_mov_b32_e32 v14, s7
	v_mad_u32_u24 v22, v10, s76, v11
	v_add_u32_e32 v12, v12, v9
	v_mad_u32_u24 v26, v8, s83, v14
	ds_read_b128 v[114:117], v22
	ds_read_b128 v[118:121], v12
	ds_read_b128 v[122:125], v22 offset:64
	ds_read_b128 v[126:129], v12 offset:64
	ds_read_b128 v[130:133], v22 offset:2304
	ds_read_b128 v[134:137], v22 offset:2368
	v_lshlrev_b32_e32 v9, 2, v13
	s_cmp_gt_i32 s48, 1
	s_cselect_b32 s14, 1, 0
	v_lshlrev_b32_e32 v13, 3, v13
	v_sub_u32_e32 v27, v8, v9
	v_add_u32_e32 v13, v26, v13
	v_lshlrev_b32_e32 v28, 5, v8
	v_add_u32_e32 v27, s14, v27
	v_add3_u32 v28, s84, v28, v9
	s_waitcnt lgkmcnt(4)
	v_mfma_f32_16x16x32_bf16 v[14:17], v[114:117], v[118:121], 0
	s_waitcnt lgkmcnt(2)
	v_mfma_f32_16x16x32_bf16 v[14:17], v[122:125], v[126:129], v[14:17]
	s_waitcnt lgkmcnt(1)
	v_mfma_f32_16x16x32_bf16 v[18:21], v[130:133], v[118:121], 0
	s_waitcnt lgkmcnt(0)
	v_mfma_f32_16x16x32_bf16 v[18:21], v[134:137], v[126:129], v[18:21]
	v_cmp_lt_i32_e32 vcc, 0, v27
	v_cmp_lt_i32_e64 s[12:13], 1, v27
	v_cmp_lt_i32_e64 s[14:15], 2, v27
	v_cmp_lt_i32_e64 s[16:17], 3, v27
	v_cndmask_b32_e32 v14, 0, v14, vcc
	v_cndmask_b32_e64 v15, 0, v15, s[12:13]
	v_cndmask_b32_e64 v16, 0, v16, s[14:15]
	v_cndmask_b32_e64 v17, 0, v17, s[16:17]
	v_cmp_lt_i32_e32 vcc, 16, v27
	v_cmp_lt_i32_e64 s[12:13], 17, v27
	v_cmp_lt_i32_e64 s[14:15], 18, v27
	v_cmp_lt_i32_e64 s[16:17], 19, v27
	v_cndmask_b32_e32 v18, 0, v18, vcc
	v_cndmask_b32_e64 v19, 0, v19, s[12:13]
	v_cndmask_b32_e64 v20, 0, v20, s[14:15]
	v_cndmask_b32_e64 v21, 0, v21, s[16:17]
	s_cmp_lg_u32 s48, 0
	s_cbranch_scc0 .Lrw_s1_f32
	v_cvt_pk_bf16_f32 v22, v14, v15
	v_cvt_pk_bf16_f32 v23, v16, v17
	v_cvt_pk_bf16_f32 v24, v18, v19
	v_cvt_pk_bf16_f32 v25, v20, v21
	ds_write_b64 v13, v[22:23]
	ds_write_b64 v13, v[24:25] offset:32
	s_branch .LBB0_534
; #define LAS __attribute__((address_space(3)))
; __device__ __forceinline__ void rwkv_chain(LAS unsigned char* lds, int cid, const bf16_t* P0, const float* mu, const float* w0, const float* w2, const float* a0, const float* a2, ...
;     ...
;               if (mat == 0) {
; #pragma unroll
;                   for (int e = 0; e < 4; ++e) NT4[e * 384 + srow * 12 + nt * 4 + fq] = acc[e]; }
;               else { LAS bf16_t* X = (mat == 1) ? NakT : (mat == 2) ? MbrT : MkrT; u32x2 o; o.x = pk2(acc[0], acc[1]); o.y = pk2(acc[2], acc[3]); *(LAS u32x2*)(X + srow * 40 + nt * 16 + fq * 4) = o; } } }
;         __syncthreads();
;         f32x4 oacc = (f32x4){0.f, 0.f, 0.f, 0.f};
;         { RW_IDS f32x4 wacc = (f32x4){0.f, 0.f, 0.f, 0.f};
; #pragma unroll
;           for (int ks = 0; ks < 2; ++ks) { const bf16x8 sf = ldsfrag(S0b, 72, vt * 16, ks * 32, fr, fq);
;               wacc = mfma16(ldsfrag(At, 72, tt2 * 16, ks * 32, fr, fq), sf, wacc); oacc = mfma16(ldsfrag(Rt, 72, tt2 * 16, ks * 32, fr, fq), sf, oacc); }
;           const bf16x8 vf = ldsfrag(VT, 40, vt * 16, 0, fr, fq);
;           wacc = mfma16(ldsfrag(NakT, 40, tt2 * 16, 0, fr, fq), vf, wacc); oacc = mfma16(ldsfrag(MkrT, 40, tt2 * 16, 0, fr, fq), vf, oacc);
; #pragma unroll
;           for (int n2 = 0; n2 < 2; ++n2) st[n2] = mfma16(ldsfrag(KtT, 40, (tt2 * 2 + n2) * 16, 0, fr, fq), vf, st[n2]);
; #pragma unroll
;           for (int e = 0; e < 4; ++e) WS[(tt2 * 16 + fq * 4 + e) * 64 + vt * 16 + fr] = wacc[e]; }
;         __syncthreads();
;         { RW_IDS if (wid < 4) { const int v = wid * 16 + (lane >> 2), p = lane & 3; const LAS float* NTp = NT4 + p * 384; float u[8];
; #pragma unroll
;             for (int j = 0; j < 8; ++j) u[j] = 0.f;
; #pragma unroll
;             for (int t = 0; t < 32; ++t) { float q0 = (p == 0) ? WS[t * 64 + v] : 0.f, q1 = 0.f;
; #pragma unroll
;                 for (int j4 = 0; j4 < ((t + 3) / 4 + 3) / 4; ++j4) { const f32x4 nv = *(const LAS f32x4*)(NTp + t * 12 + j4 * 4);
;                     q0 += u[j4 * 4] * nv[0]; q1 += u[j4 * 4 + 1] * nv[1]; q0 += u[j4 * 4 + 2] * nv[2]; q1 += u[j4 * 4 + 3] * nv[3]; }
;                 float q = q0 + q1; q += dppf<0xB1>(q); q += dppf<0x4E>(q);
;                 u[t >> 2] = ((t & 3) == p) ? q : u[t >> 2]; asm volatile("" ::: "memory"); }
; #pragma unroll
;             for (int j = 0; j < 8; ++j) Ub[v * 40 + 4 * j + p] = (bf16_t)f2bf(u[j]); } }
.Lrw_s1_f32:
	ds_write_b32 v28, v14
	ds_write_b32 v28, v15 offset:1040
	ds_write_b32 v28, v16 offset:2080
	ds_write_b32 v28, v17 offset:3120
	ds_write_b32 v28, v18 offset:16
	ds_write_b32 v28, v19 offset:1056
	ds_write_b32 v28, v20 offset:2096
	ds_write_b32 v28, v21 offset:3136
.LBB0_534:
	v_mov_b32_e32 v8, v200
	s_waitcnt lgkmcnt(0)
	s_barrier
	s_add_i32 s14, 0, 0x1d800
	v_readfirstlane_b32 s7, v8
	s_bfe_u32 s12, s7, 0x10006
	s_ashr_i32 s7, s7, 3
	v_and_b32_e32 v39, 15, v8
	v_bfe_u32 v118, v8, 4, 2
	v_bfi_b32 v8, -16, s7, v8
	v_mul_lo_u32 v28, v8, s76
	v_mul_lo_u32 v13, v8, s83
	v_lshl_or_b32 v8, s12, 5, v39
	v_lshlrev_b32_e32 v114, 4, v118
	v_lshl_or_b32 v12, s12, 4, v39
	v_mul_u32_u24_e32 v8, 0x50, v8
	v_mul_u32_u24_e32 v9, 0x48, v12
	v_add3_u32 v14, s14, v114, v8
	v_lshlrev_b32_e32 v115, 1, v9
	ds_read_b128 v[8:11], v14
	s_add_i32 s13, 0, 0x1ec00
	v_mul_u32_u24_e32 v17, 40, v12
	v_add3_u32 v16, s13, v13, v114
	s_add_i32 s13, 0, 0x23c00
	v_lshlrev_b32_e32 v24, 1, v17
	v_add3_u32 v20, s13, v24, v114
	ds_read_b128 v[12:15], v14 offset:1280
	ds_read_b128 v[16:19], v16
	ds_read_b128 v[20:23], v20
	s_add_i32 s13, 0, 0x25000
	v_add3_u32 v29, s79, v115, v114
	v_add3_u32 v24, s13, v24, v114
	ds_read_b128 v[24:27], v24
	s_waitcnt lgkmcnt(2)
	v_mfma_f32_16x16x32_bf16 v[0:3], v[8:11], v[16:19], v[0:3]
	ds_read_b128 v[8:11], v29
	v_add3_u32 v32, s85, v28, v114
	ds_read_b128 v[28:31], v29 offset:64
	v_mfma_f32_16x16x32_bf16 v[4:7], v[12:15], v[16:19], v[4:7]
	ds_read_b128 v[12:15], v32
	ds_read_b128 v[32:35], v32 offset:64
	v_add3_u32 v114, s82, v115, v114
	s_and_b32 s7, s7, -16
	s_waitcnt lgkmcnt(1)
	v_mfma_f32_16x16x32_bf16 v[8:11], v[8:11], v[12:15], 0
	s_lshl_b32 s7, s7, 2
	s_add_i32 s7, s7, 0
	s_waitcnt lgkmcnt(0)
	v_mfma_f32_16x16x32_bf16 v[8:11], v[28:31], v[32:35], v[8:11]
	ds_read_b128 v[28:31], v114
	ds_read_b128 v[114:117], v114 offset:64
	v_mfma_f32_16x16x32_bf16 v[8:11], v[20:23], v[16:19], v[8:11]
	v_lshl_add_u32 v20, v39, 2, s7
	v_lshlrev_b32_e32 v21, 10, v118
	s_lshl_b32 s7, s12, 12
	s_waitcnt lgkmcnt(1)
	v_mfma_f32_16x16x32_bf16 v[12:15], v[28:31], v[12:15], 0
	v_add3_u32 v20, v20, v21, s7
	s_nop 1
	ds_write2st64_b32 v20, v8, v9 offset0:192 offset1:193
	ds_write2st64_b32 v20, v10, v11 offset0:194 offset1:195
	s_waitcnt lgkmcnt(0)
	v_mfma_f32_16x16x32_bf16 v[8:11], v[114:117], v[32:35], v[12:15]
	s_barrier
	s_nop 1
	v_mov_b32_e32 v12, v200
	v_mfma_f32_16x16x32_bf16 v[8:11], v[24:27], v[16:19], v[8:11]
	s_nop 0
	v_readfirstlane_b32 s7, v12
	s_ashr_i32 s7, s7, 6
	s_cmp_gt_i32 s7, 3
	s_cbranch_scc1 .LBB0_488
	v_bfe_u32 v13, v12, 2, 4
	v_and_b32_e32 v14, 3, v12
	v_lshl_or_b32 v13, s7, 4, v13
	v_cmp_eq_u32_e32 vcc, 0, v14
	v_cmp_eq_u32_e64 s[14:15], 1, v14
	v_cmp_eq_u32_e64 s[12:13], 2, v14
	v_cmp_eq_u32_e64 s[16:17], 3, v14
	v_lshlrev_b32_e32 v12, 2, v13
	s_movk_i32 s7, 0x410
	v_mov_b32_e32 v15, s84
	v_mul_lo_u32 v28, v13, s83
	v_mad_u32_u24 v15, v14, s7, v15
	v_lshl_add_u32 v28, v14, 1, v28
	ds_read_b32 v122, v12 offset:49152
	ds_read_b32 v132, v12 offset:49408
	ds_read_b32 v124, v15 offset:32
	ds_read_b32 v142, v12 offset:49664
	ds_read_b32 v134, v15 offset:64
	ds_read_b32 v152, v12 offset:49920
	ds_read_b32 v144, v15 offset:96
	ds_read_b32 v162, v12 offset:50176
	ds_read_b32 v154, v15 offset:128
	ds_read_b32 v172, v12 offset:50432
	ds_read_b64 v[164:165], v15 offset:160
	s_waitcnt lgkmcnt(10)
	v_cndmask_b32_e32 v16, 0, v122, vcc
	ds_read_b32 v182, v12 offset:50688
	ds_read_b64 v[174:175], v15 offset:192
	s_waitcnt lgkmcnt(10)
	v_cndmask_b32_e32 v26, 0, v132, vcc
	v_fmac_f32_e32 v26, v16, v124
	ds_read_b32 v192, v12 offset:50944
	ds_read_b64 v[184:185], v15 offset:224
	v_add_f32_dpp v26, v26, v26 quad_perm:[1,0,3,2] row_mask:0xf bank_mask:0xf bound_ctrl:1
	s_waitcnt lgkmcnt(10)
	s_nop 0
	v_add_f32_dpp v26, v26, v26 quad_perm:[2,3,0,1] row_mask:0xf bank_mask:0xf bound_ctrl:1
	v_cndmask_b32_e32 v24, 0, v142, vcc
	v_cndmask_b32_e64 v16, v16, v26, s[14:15]
	v_fmac_f32_e32 v24, v16, v134
	ds_read_b32 v122, v12 offset:51200
	ds_read_b64 v[114:115], v15 offset:256
	v_add_f32_dpp v24, v24, v24 quad_perm:[1,0,3,2] row_mask:0xf bank_mask:0xf bound_ctrl:1
	s_waitcnt lgkmcnt(10)
	s_nop 0
	v_add_f32_dpp v24, v24, v24 quad_perm:[2,3,0,1] row_mask:0xf bank_mask:0xf bound_ctrl:1
	v_cndmask_b32_e32 v26, 0, v152, vcc
	v_cndmask_b32_e64 v16, v16, v24, s[12:13]
	v_fmac_f32_e32 v26, v16, v144
	ds_read_b32 v132, v12 offset:51456
	ds_read_b128 v[124:127], v15 offset:288
	v_add_f32_dpp v26, v26, v26 quad_perm:[1,0,3,2] row_mask:0xf bank_mask:0xf bound_ctrl:1
	s_waitcnt lgkmcnt(10)
	s_nop 0
	v_add_f32_dpp v26, v26, v26 quad_perm:[2,3,0,1] row_mask:0xf bank_mask:0xf bound_ctrl:1
	v_cndmask_b32_e32 v24, 0, v162, vcc
	v_cndmask_b32_e64 v16, v16, v26, s[16:17]
	v_fmac_f32_e32 v24, v16, v154
	ds_read_b32 v142, v12 offset:51712
	ds_read_b128 v[134:137], v15 offset:320
	v_add_f32_dpp v24, v24, v24 quad_perm:[1,0,3,2] row_mask:0xf bank_mask:0xf bound_ctrl:1
	s_waitcnt lgkmcnt(10)
	v_cndmask_b32_e32 v26, 0, v172, vcc
	v_add_f32_dpp v24, v24, v24 quad_perm:[2,3,0,1] row_mask:0xf bank_mask:0xf bound_ctrl:1
	v_fmac_f32_e32 v26, v16, v164
	v_cndmask_b32_e32 v17, 0, v24, vcc
	v_fmac_f32_e32 v26, v17, v165
	ds_read_b32 v152, v12 offset:51968
	ds_read_b128 v[144:147], v15 offset:352
	v_add_f32_dpp v26, v26, v26 quad_perm:[1,0,3,2] row_mask:0xf bank_mask:0xf bound_ctrl:1
	s_waitcnt lgkmcnt(10)
	v_cndmask_b32_e32 v24, 0, v182, vcc
	v_add_f32_dpp v26, v26, v26 quad_perm:[2,3,0,1] row_mask:0xf bank_mask:0xf bound_ctrl:1
	v_fmac_f32_e32 v24, v16, v174
	v_cndmask_b32_e64 v17, v17, v26, s[14:15]
	v_fmac_f32_e32 v24, v17, v175
	ds_read_b32 v162, v12 offset:52224
	ds_read_b128 v[154:157], v15 offset:384
	v_add_f32_dpp v24, v24, v24 quad_perm:[1,0,3,2] row_mask:0xf bank_mask:0xf bound_ctrl:1
	s_waitcnt lgkmcnt(10)
; #define LAS __attribute__((address_space(3)))
; template <int CTRL> __device__ __forceinline__ float dppf(float x) { return __builtin_bit_cast(float, __builtin_amdgcn_mov_dpp(__builtin_bit_cast(int, x), CTRL, 0xf, 0xf, true)); }
; __device__ __forceinline__ void rwkv_chain(LAS unsigned char* lds, int cid, const bf16_t* P0, const float* mu, const float* w0, const float* w2, const float* a0, const float* a2, ...
;     ...
;         { RW_IDS if (wid < 4) { const int v = wid * 16 + (lane >> 2), p = lane & 3; const LAS float* NTp = NT4 + p * 384; float u[8];
; #pragma unroll
;             for (int j = 0; j < 8; ++j) u[j] = 0.f;
; #pragma unroll
;             for (int t = 0; t < 32; ++t) { float q0 = (p == 0) ? WS[t * 64 + v] : 0.f, q1 = 0.f;
; #pragma unroll
;                 for (int j4 = 0; j4 < ((t + 3) / 4 + 3) / 4; ++j4) { const f32x4 nv = *(const LAS f32x4*)(NTp + t * 12 + j4 * 4);
;                     q0 += u[j4 * 4] * nv[0]; q1 += u[j4 * 4 + 1] * nv[1]; q0 += u[j4 * 4 + 2] * nv[2]; q1 += u[j4 * 4 + 3] * nv[3]; }
;                 float q = q0 + q1; q += dppf<0xB1>(q); q += dppf<0x4E>(q);
;                 u[t >> 2] = ((t & 3) == p) ? q : u[t >> 2]; asm volatile("" ::: "memory"); }
	v_cndmask_b32_e32 v26, 0, v192, vcc
	v_add_f32_dpp v24, v24, v24 quad_perm:[2,3,0,1] row_mask:0xf bank_mask:0xf bound_ctrl:1
	v_fmac_f32_e32 v26, v16, v184
	v_cndmask_b32_e64 v17, v17, v24, s[12:13]
	v_fmac_f32_e32 v26, v17, v185
	ds_read_b32 v172, v12 offset:52480
	ds_read_b128 v[164:167], v15 offset:416
	v_add_f32_dpp v26, v26, v26 quad_perm:[1,0,3,2] row_mask:0xf bank_mask:0xf bound_ctrl:1
	s_waitcnt lgkmcnt(10)
	v_cndmask_b32_e32 v24, 0, v122, vcc
	v_add_f32_dpp v26, v26, v26 quad_perm:[2,3,0,1] row_mask:0xf bank_mask:0xf bound_ctrl:1
	v_fmac_f32_e32 v24, v16, v114
	v_cndmask_b32_e64 v17, v17, v26, s[16:17]
	v_fmac_f32_e32 v24, v17, v115
	ds_read_b32 v182, v12 offset:52736
	ds_read_b128 v[174:177], v15 offset:448
	s_waitcnt lgkmcnt(10)
	v_add_f32_dpp v24, v24, v24 quad_perm:[1,0,3,2] row_mask:0xf bank_mask:0xf bound_ctrl:1
	v_cndmask_b32_e32 v26, 0, v132, vcc
	v_fmac_f32_e32 v26, v16, v124
	v_add_f32_dpp v24, v24, v24 quad_perm:[2,3,0,1] row_mask:0xf bank_mask:0xf bound_ctrl:1
	v_mul_f32_e32 v27, v17, v125
	v_add_f32_e32 v26, v26, v27
	v_cndmask_b32_e32 v18, 0, v24, vcc
	v_fmac_f32_e32 v26, v18, v126
	ds_read_b32 v192, v12 offset:52992
	ds_read_b128 v[184:187], v15 offset:480
	s_waitcnt lgkmcnt(10)
	v_add_f32_dpp v26, v26, v26 quad_perm:[1,0,3,2] row_mask:0xf bank_mask:0xf bound_ctrl:1
	v_cndmask_b32_e32 v24, 0, v142, vcc
	v_fmac_f32_e32 v24, v16, v134
	v_add_f32_dpp v26, v26, v26 quad_perm:[2,3,0,1] row_mask:0xf bank_mask:0xf bound_ctrl:1
	v_mul_f32_e32 v25, v17, v135
	v_add_f32_e32 v24, v24, v25
	v_cndmask_b32_e64 v18, v18, v26, s[14:15]
	v_fmac_f32_e32 v24, v18, v136
	ds_read_b32 v122, v12 offset:53248
	ds_read_b128 v[114:117], v15 offset:512
	s_waitcnt lgkmcnt(10)
	v_add_f32_dpp v24, v24, v24 quad_perm:[1,0,3,2] row_mask:0xf bank_mask:0xf bound_ctrl:1
	v_cndmask_b32_e32 v26, 0, v152, vcc
	v_fmac_f32_e32 v26, v16, v144
	v_add_f32_dpp v24, v24, v24 quad_perm:[2,3,0,1] row_mask:0xf bank_mask:0xf bound_ctrl:1
	v_mul_f32_e32 v27, v17, v145
	v_add_f32_e32 v26, v26, v27
	v_cndmask_b32_e64 v18, v18, v24, s[12:13]
	v_fmac_f32_e32 v26, v18, v146
	ds_read_b32 v132, v12 offset:53504
	ds_read_b128 v[124:127], v15 offset:544
	ds_read_b32 v128, v15 offset:560
	v_add_f32_dpp v26, v26, v26 quad_perm:[1,0,3,2] row_mask:0xf bank_mask:0xf bound_ctrl:1
	s_waitcnt lgkmcnt(11)
	v_cndmask_b32_e32 v24, 0, v162, vcc
	v_fmac_f32_e32 v24, v16, v154
	v_add_f32_dpp v26, v26, v26 quad_perm:[2,3,0,1] row_mask:0xf bank_mask:0xf bound_ctrl:1
	v_mul_f32_e32 v25, v17, v155
	v_add_f32_e32 v24, v24, v25
	v_cndmask_b32_e64 v18, v18, v26, s[16:17]
	v_fmac_f32_e32 v24, v18, v156
	ds_read_b32 v142, v12 offset:53760
	ds_read_b128 v[134:137], v15 offset:576
	ds_read_b32 v138, v15 offset:592
	v_add_f32_dpp v24, v24, v24 quad_perm:[1,0,3,2] row_mask:0xf bank_mask:0xf bound_ctrl:1
	s_waitcnt lgkmcnt(12)
	v_cndmask_b32_e32 v26, 0, v172, vcc
	v_fmac_f32_e32 v26, v16, v164
	v_add_f32_dpp v24, v24, v24 quad_perm:[2,3,0,1] row_mask:0xf bank_mask:0xf bound_ctrl:1
	v_mul_f32_e32 v27, v17, v165
	v_fmac_f32_e32 v26, v18, v166
	v_add_f32_e32 v26, v26, v27
	v_cndmask_b32_e32 v19, 0, v24, vcc
	v_fmac_f32_e32 v26, v19, v167
	ds_read_b32 v152, v12 offset:54016
	ds_read_b128 v[144:147], v15 offset:608
	ds_read_b32 v148, v15 offset:624
	v_add_f32_dpp v26, v26, v26 quad_perm:[1,0,3,2] row_mask:0xf bank_mask:0xf bound_ctrl:1
	s_waitcnt lgkmcnt(13)
	v_cndmask_b32_e32 v24, 0, v182, vcc
	v_fmac_f32_e32 v24, v16, v174
	v_add_f32_dpp v26, v26, v26 quad_perm:[2,3,0,1] row_mask:0xf bank_mask:0xf bound_ctrl:1
	v_mul_f32_e32 v25, v17, v175
	v_fmac_f32_e32 v24, v18, v176
	v_add_f32_e32 v24, v24, v25
	v_cndmask_b32_e64 v19, v19, v26, s[14:15]
	v_fmac_f32_e32 v24, v19, v177
	ds_read_b32 v162, v12 offset:54272
	ds_read_b128 v[154:157], v15 offset:640
	ds_read_b32 v158, v15 offset:656
	v_add_f32_dpp v24, v24, v24 quad_perm:[1,0,3,2] row_mask:0xf bank_mask:0xf bound_ctrl:1
	s_waitcnt lgkmcnt(14)
	v_cndmask_b32_e32 v26, 0, v192, vcc
	v_fmac_f32_e32 v26, v16, v184
	v_add_f32_dpp v24, v24, v24 quad_perm:[2,3,0,1] row_mask:0xf bank_mask:0xf bound_ctrl:1
	v_mul_f32_e32 v27, v17, v185
	v_fmac_f32_e32 v26, v18, v186
	v_add_f32_e32 v26, v26, v27
	v_cndmask_b32_e64 v19, v19, v24, s[12:13]
	v_fmac_f32_e32 v26, v19, v187
	ds_read_b32 v172, v12 offset:54528
	ds_read_b128 v[164:167], v15 offset:672
	ds_read_b64 v[168:169], v15 offset:688
	v_add_f32_dpp v26, v26, v26 quad_perm:[1,0,3,2] row_mask:0xf bank_mask:0xf bound_ctrl:1
	s_waitcnt lgkmcnt(15)
	v_cndmask_b32_e32 v24, 0, v122, vcc
	v_fmac_f32_e32 v24, v16, v114
	v_add_f32_dpp v26, v26, v26 quad_perm:[2,3,0,1] row_mask:0xf bank_mask:0xf bound_ctrl:1
	v_mul_f32_e32 v25, v17, v115
	v_fmac_f32_e32 v24, v18, v116
	v_add_f32_e32 v24, v24, v25
	v_cndmask_b32_e64 v19, v19, v26, s[16:17]
	v_fmac_f32_e32 v24, v19, v117
	ds_read_b32 v182, v12 offset:54784
	ds_read_b128 v[174:177], v15 offset:704
	ds_read_b64 v[178:179], v15 offset:720
	v_add_f32_dpp v24, v24, v24 quad_perm:[1,0,3,2] row_mask:0xf bank_mask:0xf bound_ctrl:1
	s_waitcnt lgkmcnt(15)
	v_cndmask_b32_e32 v26, 0, v132, vcc
	v_fmac_f32_e32 v26, v16, v124
	v_add_f32_dpp v24, v24, v24 quad_perm:[2,3,0,1] row_mask:0xf bank_mask:0xf bound_ctrl:1
	v_mul_f32_e32 v27, v17, v125
	v_pk_fma_f32 v[26:27], v[18:19], v[126:127], v[26:27]
	v_add_f32_e32 v26, v26, v27
	v_cndmask_b32_e32 v20, 0, v24, vcc
	v_fmac_f32_e32 v26, v20, v128
	ds_read_b32 v192, v12 offset:55040
	ds_read_b128 v[184:187], v15 offset:736
	ds_read_b64 v[188:189], v15 offset:752
	v_add_f32_dpp v26, v26, v26 quad_perm:[1,0,3,2] row_mask:0xf bank_mask:0xf bound_ctrl:1
	s_waitcnt lgkmcnt(15)
; #define LAS __attribute__((address_space(3)))
; template <int CTRL> __device__ __forceinline__ float dppf(float x) { return __builtin_bit_cast(float, __builtin_amdgcn_mov_dpp(__builtin_bit_cast(int, x), CTRL, 0xf, 0xf, true)); }
; __device__ __forceinline__ void rwkv_chain(LAS unsigned char* lds, int cid, const bf16_t* P0, const float* mu, const float* w0, const float* w2, const float* a0, const float* a2, ...
;     ...
;         { RW_IDS if (wid < 4) { const int v = wid * 16 + (lane >> 2), p = lane & 3; const LAS float* NTp = NT4 + p * 384; float u[8];
; #pragma unroll
;             for (int j = 0; j < 8; ++j) u[j] = 0.f;
; #pragma unroll
;             for (int t = 0; t < 32; ++t) { float q0 = (p == 0) ? WS[t * 64 + v] : 0.f, q1 = 0.f;
; #pragma unroll
;                 for (int j4 = 0; j4 < ((t + 3) / 4 + 3) / 4; ++j4) { const f32x4 nv = *(const LAS f32x4*)(NTp + t * 12 + j4 * 4);
;                     q0 += u[j4 * 4] * nv[0]; q1 += u[j4 * 4 + 1] * nv[1]; q0 += u[j4 * 4 + 2] * nv[2]; q1 += u[j4 * 4 + 3] * nv[3]; }
;                 float q = q0 + q1; q += dppf<0xB1>(q); q += dppf<0x4E>(q);
;                 u[t >> 2] = ((t & 3) == p) ? q : u[t >> 2]; asm volatile("" ::: "memory"); }
	v_cndmask_b32_e32 v24, 0, v142, vcc
	v_fmac_f32_e32 v24, v16, v134
	v_add_f32_dpp v26, v26, v26 quad_perm:[2,3,0,1] row_mask:0xf bank_mask:0xf bound_ctrl:1
	v_mul_f32_e32 v25, v17, v135
	v_pk_fma_f32 v[24:25], v[18:19], v[136:137], v[24:25]
	v_add_f32_e32 v24, v24, v25
	v_cndmask_b32_e64 v20, v20, v26, s[14:15]
	v_fmac_f32_e32 v24, v20, v138
	ds_read_b32 v122, v12 offset:55296
	ds_read_b128 v[114:117], v15 offset:768
	ds_read_b64 v[118:119], v15 offset:784
	v_add_f32_dpp v24, v24, v24 quad_perm:[1,0,3,2] row_mask:0xf bank_mask:0xf bound_ctrl:1
	s_waitcnt lgkmcnt(15)
	v_cndmask_b32_e32 v26, 0, v152, vcc
	v_fmac_f32_e32 v26, v16, v144
	v_add_f32_dpp v24, v24, v24 quad_perm:[2,3,0,1] row_mask:0xf bank_mask:0xf bound_ctrl:1
	v_mul_f32_e32 v27, v17, v145
	v_pk_fma_f32 v[26:27], v[18:19], v[146:147], v[26:27]
	v_add_f32_e32 v26, v26, v27
	v_cndmask_b32_e64 v20, v20, v24, s[12:13]
	v_fmac_f32_e32 v26, v20, v148
	ds_read_b32 v132, v12 offset:55552
	ds_read_b128 v[124:127], v15 offset:800
	ds_read_b128 v[128:131], v15 offset:816
	v_add_f32_dpp v26, v26, v26 quad_perm:[1,0,3,2] row_mask:0xf bank_mask:0xf bound_ctrl:1
	s_waitcnt lgkmcnt(15)
	v_cndmask_b32_e32 v24, 0, v162, vcc
	v_fmac_f32_e32 v24, v16, v154
	v_add_f32_dpp v26, v26, v26 quad_perm:[2,3,0,1] row_mask:0xf bank_mask:0xf bound_ctrl:1
	v_mul_f32_e32 v25, v17, v155
	v_pk_fma_f32 v[24:25], v[18:19], v[156:157], v[24:25]
	v_add_f32_e32 v24, v24, v25
	v_cndmask_b32_e64 v20, v20, v26, s[16:17]
	v_fmac_f32_e32 v24, v20, v158
	ds_read_b32 v142, v12 offset:55808
	ds_read_b128 v[134:137], v15 offset:832
	ds_read_b128 v[138:141], v15 offset:848
	s_waitcnt lgkmcnt(15)
	v_add_f32_dpp v24, v24, v24 quad_perm:[1,0,3,2] row_mask:0xf bank_mask:0xf bound_ctrl:1
	v_cndmask_b32_e32 v26, 0, v172, vcc
	v_fmac_f32_e32 v26, v16, v164
	v_mul_f32_e32 v27, v17, v165
	v_add_f32_dpp v24, v24, v24 quad_perm:[2,3,0,1] row_mask:0xf bank_mask:0xf bound_ctrl:1
	v_pk_fma_f32 v[26:27], v[18:19], v[166:167], v[26:27]
	v_fmac_f32_e32 v26, v20, v168
	v_add_f32_e32 v26, v26, v27
	v_cndmask_b32_e32 v21, 0, v24, vcc
	v_fmac_f32_e32 v26, v21, v169
	ds_read_b32 v152, v12 offset:56064
	ds_read_b128 v[144:147], v15 offset:864
	ds_read_b128 v[148:151], v15 offset:880
	s_waitcnt lgkmcnt(15)
	v_add_f32_dpp v26, v26, v26 quad_perm:[1,0,3,2] row_mask:0xf bank_mask:0xf bound_ctrl:1
	v_cndmask_b32_e32 v24, 0, v182, vcc
	v_fmac_f32_e32 v24, v16, v174
	v_mul_f32_e32 v25, v17, v175
	v_add_f32_dpp v26, v26, v26 quad_perm:[2,3,0,1] row_mask:0xf bank_mask:0xf bound_ctrl:1
	v_pk_fma_f32 v[24:25], v[18:19], v[176:177], v[24:25]
	v_fmac_f32_e32 v24, v20, v178
	v_add_f32_e32 v24, v24, v25
	v_cndmask_b32_e64 v21, v21, v26, s[14:15]
	v_fmac_f32_e32 v24, v21, v179
	ds_read_b32 v162, v12 offset:56320
	ds_read_b128 v[154:157], v15 offset:896
	ds_read_b128 v[158:161], v15 offset:912
	s_waitcnt lgkmcnt(15)
	v_add_f32_dpp v24, v24, v24 quad_perm:[1,0,3,2] row_mask:0xf bank_mask:0xf bound_ctrl:1
	v_cndmask_b32_e32 v26, 0, v192, vcc
	v_fmac_f32_e32 v26, v16, v184
	v_mul_f32_e32 v27, v17, v185
	v_add_f32_dpp v24, v24, v24 quad_perm:[2,3,0,1] row_mask:0xf bank_mask:0xf bound_ctrl:1
	v_pk_fma_f32 v[26:27], v[18:19], v[186:187], v[26:27]
	v_fmac_f32_e32 v26, v20, v188
	v_add_f32_e32 v26, v26, v27
	v_cndmask_b32_e64 v21, v21, v24, s[12:13]
	v_fmac_f32_e32 v26, v21, v189
	ds_read_b32 v172, v12 offset:56576
	ds_read_b128 v[164:167], v15 offset:928
	ds_read_b128 v[168:171], v15 offset:944
	s_waitcnt lgkmcnt(15)
	v_add_f32_dpp v26, v26, v26 quad_perm:[1,0,3,2] row_mask:0xf bank_mask:0xf bound_ctrl:1
	v_cndmask_b32_e32 v24, 0, v122, vcc
	v_fmac_f32_e32 v24, v16, v114
	v_mul_f32_e32 v25, v17, v115
	v_add_f32_dpp v26, v26, v26 quad_perm:[2,3,0,1] row_mask:0xf bank_mask:0xf bound_ctrl:1
	v_pk_fma_f32 v[24:25], v[18:19], v[116:117], v[24:25]
	v_fmac_f32_e32 v24, v20, v118
	v_add_f32_e32 v24, v24, v25
	v_cndmask_b32_e64 v21, v21, v26, s[16:17]
	v_fmac_f32_e32 v24, v21, v119
	ds_read_b32 v182, v12 offset:56832
	ds_read_b128 v[174:177], v15 offset:960
	ds_read_b128 v[178:181], v15 offset:976
	s_waitcnt lgkmcnt(15)
; #define LAS __attribute__((address_space(3)))
; __device__ __forceinline__ unsigned f2bf(float f) { return pk2(f, 0.f) & 0xffffu; }
; template <int CTRL> __device__ __forceinline__ float dppf(float x) { return __builtin_bit_cast(float, __builtin_amdgcn_mov_dpp(__builtin_bit_cast(int, x), CTRL, 0xf, 0xf, true)); }
; __device__ __forceinline__ void rwkv_chain(LAS unsigned char* lds, int cid, const bf16_t* P0, const float* mu, const float* w0, const float* w2, const float* a0, const float* a2, ...
;     ...
;         { RW_IDS if (wid < 4) { const int v = wid * 16 + (lane >> 2), p = lane & 3; const LAS float* NTp = NT4 + p * 384; float u[8];
; #pragma unroll
;             for (int j = 0; j < 8; ++j) u[j] = 0.f;
; #pragma unroll
;             for (int t = 0; t < 32; ++t) { float q0 = (p == 0) ? WS[t * 64 + v] : 0.f, q1 = 0.f;
; #pragma unroll
;                 for (int j4 = 0; j4 < ((t + 3) / 4 + 3) / 4; ++j4) { const f32x4 nv = *(const LAS f32x4*)(NTp + t * 12 + j4 * 4);
;                     q0 += u[j4 * 4] * nv[0]; q1 += u[j4 * 4 + 1] * nv[1]; q0 += u[j4 * 4 + 2] * nv[2]; q1 += u[j4 * 4 + 3] * nv[3]; }
;                 float q = q0 + q1; q += dppf<0xB1>(q); q += dppf<0x4E>(q);
;                 u[t >> 2] = ((t & 3) == p) ? q : u[t >> 2]; asm volatile("" ::: "memory"); }
; #pragma unroll
;             for (int j = 0; j < 8; ++j) Ub[v * 40 + 4 * j + p] = (bf16_t)f2bf(u[j]); } }
	v_add_f32_dpp v24, v24, v24 quad_perm:[1,0,3,2] row_mask:0xf bank_mask:0xf bound_ctrl:1
	v_cndmask_b32_e32 v26, 0, v132, vcc
	v_fmac_f32_e32 v26, v16, v124
	v_mul_f32_e32 v27, v17, v125
	v_add_f32_dpp v24, v24, v24 quad_perm:[2,3,0,1] row_mask:0xf bank_mask:0xf bound_ctrl:1
	v_pk_fma_f32 v[26:27], v[18:19], v[126:127], v[26:27]
	v_pk_fma_f32 v[26:27], v[20:21], v[128:129], v[26:27]
	v_add_f32_e32 v26, v26, v27
	v_cndmask_b32_e32 v22, 0, v24, vcc
	v_fmac_f32_e32 v26, v22, v130
	ds_read_b32 v192, v12 offset:57088
	ds_read_b128 v[184:187], v15 offset:992
	ds_read_b128 v[188:191], v15 offset:1008
	s_waitcnt lgkmcnt(15)
	v_add_f32_dpp v26, v26, v26 quad_perm:[1,0,3,2] row_mask:0xf bank_mask:0xf bound_ctrl:1
	v_cndmask_b32_e32 v24, 0, v142, vcc
	v_fmac_f32_e32 v24, v16, v134
	v_mul_f32_e32 v25, v17, v135
	v_add_f32_dpp v26, v26, v26 quad_perm:[2,3,0,1] row_mask:0xf bank_mask:0xf bound_ctrl:1
	v_pk_fma_f32 v[24:25], v[18:19], v[136:137], v[24:25]
	v_pk_fma_f32 v[24:25], v[20:21], v[138:139], v[24:25]
	v_add_f32_e32 v24, v24, v25
	v_cndmask_b32_e64 v22, v22, v26, s[14:15]
	v_fmac_f32_e32 v24, v22, v140
	s_waitcnt lgkmcnt(12)
	v_cndmask_b32_e32 v26, 0, v152, vcc
	v_fmac_f32_e32 v26, v16, v144
	v_add_f32_dpp v24, v24, v24 quad_perm:[1,0,3,2] row_mask:0xf bank_mask:0xf bound_ctrl:1
	v_mul_f32_e32 v27, v17, v145
	v_pk_fma_f32 v[26:27], v[18:19], v[146:147], v[26:27]
	v_add_f32_dpp v24, v24, v24 quad_perm:[2,3,0,1] row_mask:0xf bank_mask:0xf bound_ctrl:1
	v_pk_fma_f32 v[26:27], v[20:21], v[148:149], v[26:27]
	v_add_f32_e32 v26, v26, v27
	v_cndmask_b32_e64 v22, v22, v24, s[12:13]
	v_fmac_f32_e32 v26, v22, v150
	s_waitcnt lgkmcnt(9)
	v_cndmask_b32_e32 v24, 0, v162, vcc
	v_fmac_f32_e32 v24, v16, v154
	v_add_f32_dpp v26, v26, v26 quad_perm:[1,0,3,2] row_mask:0xf bank_mask:0xf bound_ctrl:1
	v_mul_f32_e32 v25, v17, v155
	v_pk_fma_f32 v[24:25], v[18:19], v[156:157], v[24:25]
	v_add_f32_dpp v26, v26, v26 quad_perm:[2,3,0,1] row_mask:0xf bank_mask:0xf bound_ctrl:1
	v_pk_fma_f32 v[24:25], v[20:21], v[158:159], v[24:25]
	v_add_f32_e32 v24, v24, v25
	v_cndmask_b32_e64 v22, v22, v26, s[16:17]
	v_fmac_f32_e32 v24, v22, v160
	s_waitcnt lgkmcnt(6)
	v_cndmask_b32_e32 v26, 0, v172, vcc
	v_fmac_f32_e32 v26, v16, v164
	v_add_f32_dpp v24, v24, v24 quad_perm:[1,0,3,2] row_mask:0xf bank_mask:0xf bound_ctrl:1
	v_mul_f32_e32 v27, v17, v165
	v_pk_fma_f32 v[26:27], v[18:19], v[166:167], v[26:27]
	v_pk_fma_f32 v[26:27], v[20:21], v[168:169], v[26:27]
	v_add_f32_dpp v24, v24, v24 quad_perm:[2,3,0,1] row_mask:0xf bank_mask:0xf bound_ctrl:1
	v_fmac_f32_e32 v26, v22, v170
	v_add_f32_e32 v26, v26, v27
	v_cndmask_b32_e32 v23, 0, v24, vcc
	v_fmac_f32_e32 v26, v23, v171
	s_waitcnt lgkmcnt(3)
	v_cndmask_b32_e32 v24, 0, v182, vcc
	v_fmac_f32_e32 v24, v16, v174
	v_add_f32_dpp v26, v26, v26 quad_perm:[1,0,3,2] row_mask:0xf bank_mask:0xf bound_ctrl:1
	v_mul_f32_e32 v25, v17, v175
	v_pk_fma_f32 v[24:25], v[18:19], v[176:177], v[24:25]
	v_pk_fma_f32 v[24:25], v[20:21], v[178:179], v[24:25]
	v_add_f32_dpp v26, v26, v26 quad_perm:[2,3,0,1] row_mask:0xf bank_mask:0xf bound_ctrl:1
	v_fmac_f32_e32 v24, v22, v180
	v_add_f32_e32 v24, v24, v25
	v_cndmask_b32_e64 v23, v23, v26, s[14:15]
	v_fmac_f32_e32 v24, v23, v181
	s_waitcnt lgkmcnt(0)
	v_cndmask_b32_e32 v26, 0, v192, vcc
	v_fmac_f32_e32 v26, v16, v184
	v_add_f32_dpp v24, v24, v24 quad_perm:[1,0,3,2] row_mask:0xf bank_mask:0xf bound_ctrl:1
	v_mul_f32_e32 v27, v17, v185
	v_pk_fma_f32 v[26:27], v[18:19], v[186:187], v[26:27]
	v_pk_fma_f32 v[26:27], v[20:21], v[188:189], v[26:27]
	v_add_f32_dpp v24, v24, v24 quad_perm:[2,3,0,1] row_mask:0xf bank_mask:0xf bound_ctrl:1
	v_fmac_f32_e32 v26, v22, v190
	v_add_f32_e32 v26, v26, v27
	v_cndmask_b32_e64 v23, v23, v24, s[12:13]
	v_fmac_f32_e32 v26, v23, v191
	s_nop 1
	v_add_f32_dpp v26, v26, v26 quad_perm:[1,0,3,2] row_mask:0xf bank_mask:0xf bound_ctrl:1
	s_nop 1
	v_add_f32_dpp v26, v26, v26 quad_perm:[2,3,0,1] row_mask:0xf bank_mask:0xf bound_ctrl:1
	v_cndmask_b32_e64 v23, v23, v26, s[16:17]
	v_cvt_pk_bf16_f32 v30, v16, v16
	ds_write_b16 v28, v30 offset:57344
	v_cvt_pk_bf16_f32 v31, v17, v17
	ds_write_b16 v28, v31 offset:57352
	v_cvt_pk_bf16_f32 v30, v18, v18
	ds_write_b16 v28, v30 offset:57360
	v_cvt_pk_bf16_f32 v31, v19, v19
	ds_write_b16 v28, v31 offset:57368
	v_cvt_pk_bf16_f32 v30, v20, v20
	ds_write_b16 v28, v30 offset:57376
	v_cvt_pk_bf16_f32 v31, v21, v21
	ds_write_b16 v28, v31 offset:57384
	v_cvt_pk_bf16_f32 v30, v22, v22
	ds_write_b16 v28, v30 offset:57392
	v_cvt_pk_bf16_f32 v31, v23, v23
	ds_write_b16 v28, v31 offset:57400
	s_branch .LBB0_488
